# late weight-transpose loops: next tile loads stay in flight across LDS phase and descriptor compute; x to bf16 conversion loop unrolled 4x (8 loads in flight)
# speedup vs baseline: 1.0026x; 1.0017x over previous
.LBB0_5:
	s_or_b64 exec, exec, s[4:5]
	s_load_dwordx2 s[72:73], s[0:1], 0x310
	s_load_dword s80, s[0:1], 0x318
	s_add_u32 s2, s0, 0x318
	s_addc_u32 s3, s1, 0
	v_writelane_b32 v250, s2, 0
	s_waitcnt lgkmcnt(0)
	s_cmp_lt_i32 s72, 1
	v_writelane_b32 v250, s3, 1
	s_cselect_b64 s[2:3], -1, 0
	s_cmp_gt_i32 s73, 0
	s_cselect_b64 s[4:5], -1, 0
	s_and_b64 s[4:5], s[2:3], s[4:5]
	s_andn2_b64 vcc, exec, s[4:5]
	s_cbranch_vccnz .LBB0_27
	s_mov_b32 s77, 0
	s_lshl_b64 s[2:3], s[76:77], 9
	v_or_b32_e32 v2, s2, v0
	v_mov_b32_e32 v3, s3
	s_mov_b32 s81, s77
	s_mov_b64 s[2:3], 0x800000
	v_mov_b32_e32 v7, 0
	s_lshl_b64 s[10:11], s[80:81], 9
	v_cmp_gt_u64_e32 vcc, s[2:3], v[2:3]
	s_and_saveexec_b64 s[8:9], vcc
	s_cbranch_execz .LBB0_9
	s_load_dwordx2 s[2:3], s[0:1], 0x0
	s_lshl_b64 s[12:13], s[76:77], 14
	v_lshlrev_b32_e32 v6, 5, v0
	s_mov_b64 s[16:17], 0
	s_mov_b64 s[18:19], 0x7fffff
	s_waitcnt lgkmcnt(0)
	s_add_u32 s2, s2, s12
	s_addc_u32 s3, s3, s13
	s_lshl_b64 s[12:13], s[80:81], 14
	s_lshl_b64 s[14:15], s[76:77], 13
	v_lshl_add_u64 v[4:5], s[2:3], 0, v[6:7]
	s_add_u32 s2, s74, s14
	v_lshlrev_b32_e32 v6, 4, v0
	s_addc_u32 s3, s75, s15
	v_lshl_add_u64 v[6:7], s[2:3], 0, v[6:7]
	s_mov_b64 s[2:3], 0xb510000
	v_lshl_add_u64 v[4:5], v[4:5], 0, 16
	v_lshl_add_u64 v[6:7], v[6:7], 0, s[2:3]
	s_lshl_b64 s[14:15], s[80:81], 13
	v_mov_b64_e32 v[8:9], v[2:3]
	s_lshl_b64 s[20:21], s[10:11], 1
	s_add_u32 s20, s20, s10
	s_addc_u32 s21, s21, s11
	s_lshl_b64 s[22:23], s[10:11], 2
.Lxc_loop4:
	v_lshl_add_u64 v[18:19], v[8:9], 0, s[20:21]
	v_cmp_lt_u64_e32 vcc, s[18:19], v[18:19]
	s_cbranch_vccnz .Lxc_tail
	global_load_dwordx4 v[10:13], v[4:5], off offset:-16
	global_load_dwordx4 v[14:17], v[4:5], off
	v_lshl_add_u64 v[18:19], v[4:5], 0, s[12:13]
	global_load_dwordx4 v[20:23], v[18:19], off offset:-16
	global_load_dwordx4 v[24:27], v[18:19], off
	v_lshl_add_u64 v[18:19], v[18:19], 0, s[12:13]
	global_load_dwordx4 v[28:31], v[18:19], off offset:-16
	global_load_dwordx4 v[32:35], v[18:19], off
	v_lshl_add_u64 v[18:19], v[18:19], 0, s[12:13]
	global_load_dwordx4 v[36:39], v[18:19], off offset:-16
	global_load_dwordx4 v[40:43], v[18:19], off
	v_lshl_add_u64 v[4:5], v[18:19], 0, s[12:13]
	v_lshl_add_u64 v[8:9], v[8:9], 0, s[22:23]
	s_waitcnt vmcnt(6)
	v_cvt_pk_bf16_f32 v10, v10, v11
	v_cvt_pk_bf16_f32 v11, v12, v13
	v_cvt_pk_bf16_f32 v12, v14, v15
	v_cvt_pk_bf16_f32 v13, v16, v17
	global_store_dwordx4 v[6:7], v[10:13], off
	v_lshl_add_u64 v[44:45], v[6:7], 0, s[14:15]
	s_waitcnt vmcnt(5)
	v_cvt_pk_bf16_f32 v20, v20, v21
	v_cvt_pk_bf16_f32 v21, v22, v23
	v_cvt_pk_bf16_f32 v22, v24, v25
	v_cvt_pk_bf16_f32 v23, v26, v27
	global_store_dwordx4 v[44:45], v[20:23], off
	v_lshl_add_u64 v[44:45], v[44:45], 0, s[14:15]
	s_waitcnt vmcnt(4)
	v_cvt_pk_bf16_f32 v28, v28, v29
	v_cvt_pk_bf16_f32 v29, v30, v31
	v_cvt_pk_bf16_f32 v30, v32, v33
	v_cvt_pk_bf16_f32 v31, v34, v35
	global_store_dwordx4 v[44:45], v[28:31], off
	v_lshl_add_u64 v[44:45], v[44:45], 0, s[14:15]
	s_waitcnt vmcnt(3)
	v_cvt_pk_bf16_f32 v36, v36, v37
	v_cvt_pk_bf16_f32 v37, v38, v39
	v_cvt_pk_bf16_f32 v38, v40, v41
	v_cvt_pk_bf16_f32 v39, v42, v43
	global_store_dwordx4 v[44:45], v[36:39], off
	v_lshl_add_u64 v[6:7], v[44:45], 0, s[14:15]
	s_branch .Lxc_loop4
.Lxc_tail:
	v_cmp_ge_u64_e32 vcc, s[18:19], v[8:9]
	s_and_b64 exec, exec, vcc
	s_cbranch_execz .LBB0_9

.LBB0_106:
	s_or_b64 exec, exec, s[18:19]
	v_lshlrev_b32_e32 v10, 3, v0
	v_and_b32_e32 v10, 56, v10
	v_lshl_add_u32 v11, v10, 2, 0
	v_lshl_add_u32 v12, v1, 2, 0
	v_mul_u32_u24_e32 v13, 0x104, v149
	v_mov_b32_e32 v21, 0
	v_mul_u32_u24_e32 v14, 0x104, v18
	s_movk_i32 s25, 0x9a00
	v_lshlrev_b32_e32 v20, 2, v18
	v_add_u32_e32 v19, v12, v14
	v_add_u32_e32 v24, v11, v13
	v_lshlrev_b32_e32 v22, 1, v10
	v_mov_b32_e32 v23, v21
	s_mov_b32 s98, 0
	s_branch .LBB0_108
.LBB0_107:
	s_or_b64 exec, exec, s[10:11]
	s_load_dwordx2 s[10:11], s[18:19], 0xf0
	ds_write2_b32 v19, v2, v6 offset1:32
	ds_write2_b32 v19, v3, v7 offset0:65 offset1:97
	ds_write2_b32 v19, v4, v8 offset0:130 offset1:162
	ds_write2_b32 v19, v5, v9 offset0:195 offset1:227
	s_waitcnt lgkmcnt(0)
	s_barrier
	ds_read2_b32 v[2:3], v24 offset1:1
	ds_read2_b32 v[4:5], v24 offset0:2 offset1:3
	ds_read2_b32 v[6:7], v24 offset0:4 offset1:5
	ds_read2_b32 v[8:9], v24 offset0:6 offset1:7
	s_waitcnt lgkmcnt(3)
	v_cvt_pk_bf16_f32 v2, v2, v3
	s_waitcnt lgkmcnt(2)
	v_cvt_pk_bf16_f32 v3, v4, v5
	s_waitcnt lgkmcnt(1)
	v_cvt_pk_bf16_f32 v4, v6, v7
	v_add_u32_e32 v6, s24, v149
	v_mad_i64_i32 v[6:7], s[18:19], v6, s15, 0
	v_lshl_add_u64 v[6:7], v[6:7], 1, s[12:13]
	s_ashr_i32 s15, s14, 31
	v_lshl_add_u64 v[6:7], s[14:15], 1, v[6:7]
	s_waitcnt lgkmcnt(0)
	v_cvt_pk_bf16_f32 v5, v8, v9
	v_lshl_add_u64 v[6:7], v[6:7], 0, v[22:23]
	global_store_dwordx4 v[6:7], v[2:5], off
	s_andn2_b64 vcc, exec, s[16:17]
	s_mov_b32 s14, s27
	s_mov_b32 s24, s26
	s_mov_b32 s15, s8
	s_mov_b64 s[12:13], s[10:11]
	s_barrier
	s_cbranch_vccz .LBB0_112
.LBB0_108:
	s_mov_b32 s8, s3
	s_add_i32 s3, s3, 1
	s_cmp_ge_i32 s3, s2
	s_cselect_b64 s[16:17], -1, 0
	s_cmp_lt_i32 s3, s2
	s_cselect_b32 s8, s3, s8
	s_cmpk_lt_u32 s8, 0x6600
	s_cselect_b32 s9, 12, 13
	s_add_i32 s10, s8, 0xfffff000
	s_cmpk_lt_u32 s10, 0x5600
	s_cselect_b32 s10, 0xfffff000, s25
	s_cmpk_gt_i32 s8, 0xfff
	s_cselect_b32 s9, s9, 11
	s_cselect_b32 s10, s10, 0
	s_add_i32 s22, s10, s8
	s_mul_i32 s9, s9, 40
	s_add_u32 s18, s0, s9
	s_addc_u32 s19, s1, 0
	s_load_dwordx4 s[8:11], s[18:19], 0xf8
	s_load_dwordx2 s[20:21], s[18:19], 0xe0
	s_abs_i32 s26, s22
	s_waitcnt lgkmcnt(0)
	s_ashr_i32 s23, s10, 6
	s_abs_i32 s10, s23
	v_cvt_f32_u32_e32 v251, s10
	s_sub_i32 s28, 0, s10
	s_xor_b32 s27, s22, s23
	s_ashr_i32 s27, s27, 31
	v_rcp_iflag_f32_e32 v251, v251
	s_nop 0
	v_mul_f32_e32 v251, 0x4f7ffffe, v251
	v_cvt_u32_f32_e32 v251, v251
	s_nop 0
	v_readfirstlane_b32 s29, v251
	s_mul_i32 s28, s28, s29
	s_mul_hi_u32 s28, s29, s28
	s_add_i32 s29, s29, s28
	s_mul_hi_u32 s28, s26, s29
	s_mul_i32 s29, s28, s10
	s_sub_i32 s26, s26, s29
	s_add_i32 s30, s28, 1
	s_sub_i32 s29, s26, s10
	s_cmp_ge_u32 s26, s10
	s_cselect_b32 s28, s30, s28
	s_cselect_b32 s26, s29, s26
	s_add_i32 s29, s28, 1
	s_cmp_ge_u32 s26, s10
	s_cselect_b32 s10, s29, s28
	s_xor_b32 s10, s10, s27
	s_sub_i32 s10, s10, s27
	s_mul_i32 s23, s10, s23
	s_sub_i32 s23, s22, s23
	s_lshl_b32 s26, s23, 6
	s_cmp_lg_u32 s11, 1
	s_mov_b32 s22, s26
	s_cbranch_scc1 .LBB0_110
	s_load_dwordx2 s[28:29], s[18:19], 0xe8
	s_lshl_b32 s22, s23, 5
	s_and_b32 s11, s23, 2
	s_and_b32 s22, s22, 0xffffff80
	s_and_b32 s23, s26, 64
	s_or_b32 s22, s22, s23
	s_cmp_eq_u32 s11, 0
	s_waitcnt lgkmcnt(0)
	s_cselect_b32 s21, s21, s29
	s_cselect_b32 s20, s20, s28
.LBB0_110:
	s_waitcnt vmcnt(0)
	s_cmp_eq_u32 s98, 0
	s_cbranch_scc1 .Ltsb_skip_0
	v_mov_b32_e32 v6, v14
	v_mov_b32_e32 v7, v15
	v_mov_b32_e32 v8, v16
	v_mov_b32_e32 v9, v17
	v_mov_b32_e32 v2, v10
	v_mov_b32_e32 v3, v11
	v_mov_b32_e32 v4, v12
	v_mov_b32_e32 v5, v13
.Ltsb_skip_0:
	s_mov_b32 s98, 1
	v_add_u32_e32 v10, s22, v18
	s_lshl_b32 s27, s10, 6
	v_cmp_gt_i32_e32 vcc, s9, v10
	v_mov_b32_e32 v10, 0
	v_mov_b32_e32 v11, 0
	v_mov_b32_e32 v12, 0
	v_mov_b32_e32 v13, 0
	v_mov_b32_e32 v14, 0
	v_mov_b32_e32 v15, 0
	v_mov_b32_e32 v16, 0
	v_mov_b32_e32 v17, 0
	s_and_saveexec_b64 s[10:11], vcc
	s_cbranch_execz .LBB0_107
	v_or_b32_e32 v12, s27, v1
	v_mad_i64_i32 v[10:11], s[28:29], v12, s9, 0
	s_ashr_i32 s23, s22, 31
	v_lshl_add_u64 v[10:11], v[10:11], 2, s[20:21]
	s_lshl_b64 s[22:23], s[22:23], 2
	v_lshl_add_u64 v[10:11], v[10:11], 0, s[22:23]
	v_lshl_add_u64 v[26:27], v[10:11], 0, v[20:21]
	v_add_u32_e32 v10, 32, v12
	v_mad_i64_i32 v[10:11], s[28:29], v10, s9, 0
	v_lshl_add_u64 v[10:11], v[10:11], 2, s[20:21]
	v_lshl_add_u64 v[10:11], v[10:11], 0, s[22:23]
	v_lshl_add_u64 v[28:29], v[10:11], 0, v[20:21]
	global_load_dwordx4 v[10:13], v[26:27], off
	global_load_dwordx4 v[14:17], v[28:29], off
	s_branch .LBB0_107
.LBB0_112:
	s_waitcnt vmcnt(0)
	s_cmp_gt_i32 s73, 2
	s_cselect_b64 s[8:9], -1, 0
	s_and_b64 s[2:3], s[4:5], s[8:9]
	s_andn2_b64 vcc, exec, s[2:3]
	s_cbranch_vccnz .LBB0_166
	s_waitcnt vmcnt(0)
	s_waitcnt vmcnt(0)
	s_barrier
	s_and_saveexec_b64 s[4:5], s[86:87]
	s_cbranch_execz .LBB0_165
	s_add_i32 s2, 0, 0x25f00
	v_mov_b32_e32 v1, s2
	s_waitcnt vmcnt(0) expcnt(0) lgkmcnt(0)
	ds_read_b32 v3, v1
	s_add_i32 s2, 0, 0x25f04
	v_mov_b32_e32 v1, s2
	ds_read_b32 v1, v1
	s_waitcnt lgkmcnt(1)
	v_cmp_ne_u32_e32 vcc, 0, v3
	s_cbranch_vccnz .LBB0_129
	v_readlane_b32 s10, v250, 0
	v_readlane_b32 s11, v250, 1
	s_load_dwordx2 s[2:3], s[10:11], 0x4
	s_add_u32 s10, s74, 0x1000
	s_addc_u32 s11, s75, 0
	s_add_u32 s12, s74, 0x1100
	s_addc_u32 s13, s75, 0
	s_add_u32 s14, s74, 0x1200
	s_addc_u32 s15, s75, 0
	s_waitcnt lgkmcnt(0)
	s_mul_i32 s2, s2, s80
	s_add_u32 s16, s74, 0x1300
	s_mul_i32 s2, s2, s3
	s_addc_u32 s17, s75, 0
	s_mov_b32 s3, 1
	v_mov_b32_e32 v17, 0
	s_branch .LBB0_117

.LBB0_873:
	s_or_b64 exec, exec, s[16:17]
	v_lshlrev_b32_e32 v10, 3, v0
	v_and_b32_e32 v10, 56, v10
	v_lshl_add_u32 v11, v10, 2, 0
	v_lshl_add_u32 v12, v19, 2, 0
	v_mul_u32_u24_e32 v13, 0x104, v148
	v_mov_b32_e32 v21, 0
	v_mul_u32_u24_e32 v14, 0x104, v18
	s_movk_i32 s23, 0x9a00
	v_lshlrev_b32_e32 v20, 2, v18
	v_add_u32_e32 v24, v12, v14
	v_add_u32_e32 v25, v11, v13
	v_lshlrev_b32_e32 v22, 1, v10
	v_mov_b32_e32 v23, v21
	s_mov_b32 s98, 0
	s_branch .LBB0_875
.LBB0_874:
	s_or_b64 exec, exec, s[10:11]
	s_load_dwordx2 s[10:11], s[16:17], 0xf0
	ds_write2_b32 v24, v2, v6 offset1:32
	ds_write2_b32 v24, v3, v7 offset0:65 offset1:97
	ds_write2_b32 v24, v4, v8 offset0:130 offset1:162
	ds_write2_b32 v24, v5, v9 offset0:195 offset1:227
	s_waitcnt lgkmcnt(0)
	s_barrier
	ds_read2_b32 v[2:3], v25 offset1:1
	ds_read2_b32 v[4:5], v25 offset0:2 offset1:3
	ds_read2_b32 v[6:7], v25 offset0:4 offset1:5
	ds_read2_b32 v[8:9], v25 offset0:6 offset1:7
	s_waitcnt lgkmcnt(3)
	v_cvt_pk_bf16_f32 v2, v2, v3
	s_waitcnt lgkmcnt(2)
	v_cvt_pk_bf16_f32 v3, v4, v5
	s_waitcnt lgkmcnt(1)
	v_cvt_pk_bf16_f32 v4, v6, v7
	v_add_u32_e32 v6, s22, v148
	v_mad_i64_i32 v[6:7], s[16:17], v6, s13, 0
	v_lshl_add_u64 v[6:7], v[6:7], 1, s[6:7]
	s_ashr_i32 s13, s12, 31
	v_lshl_add_u64 v[6:7], s[12:13], 1, v[6:7]
	s_waitcnt lgkmcnt(0)
	v_cvt_pk_bf16_f32 v5, v8, v9
	v_lshl_add_u64 v[6:7], v[6:7], 0, v[22:23]
	global_store_dwordx4 v[6:7], v[2:5], off
	s_andn2_b64 vcc, exec, s[14:15]
	s_mov_b32 s12, s25
	s_mov_b32 s22, s24
	s_mov_b32 s13, s8
	s_mov_b64 s[6:7], s[10:11]
	s_barrier
	s_cbranch_vccz .LBB0_879
.LBB0_875:
	s_mov_b32 s8, s3
	s_add_i32 s3, s3, 1
	s_cmp_ge_i32 s3, s2
	s_cselect_b64 s[14:15], -1, 0
	s_cmp_lt_i32 s3, s2
	s_cselect_b32 s8, s3, s8
	s_cmpk_lt_u32 s8, 0x6600
	s_cselect_b32 s9, 12, 13
	s_add_i32 s10, s8, 0xfffff000
	s_cmpk_lt_u32 s10, 0x5600
	s_cselect_b32 s10, 0xfffff000, s23
	s_cmpk_gt_i32 s8, 0xfff
	s_cselect_b32 s9, s9, 11
	s_cselect_b32 s10, s10, 0
	s_add_i32 s20, s10, s8
	s_mul_i32 s9, s9, 40
	s_add_u32 s16, s0, s9
	s_addc_u32 s17, s1, 0
	s_load_dwordx4 s[8:11], s[16:17], 0xf8
	s_load_dwordx2 s[18:19], s[16:17], 0xe0
	s_abs_i32 s24, s20
	s_waitcnt lgkmcnt(0)
	s_ashr_i32 s21, s10, 6
	s_abs_i32 s10, s21
	v_cvt_f32_u32_e32 v251, s10
	s_sub_i32 s26, 0, s10
	s_xor_b32 s25, s20, s21
	s_ashr_i32 s25, s25, 31
	v_rcp_iflag_f32_e32 v251, v251
	s_nop 0
	v_mul_f32_e32 v251, 0x4f7ffffe, v251
	v_cvt_u32_f32_e32 v251, v251
	s_nop 0
	v_readfirstlane_b32 s27, v251
	s_mul_i32 s26, s26, s27
	s_mul_hi_u32 s26, s27, s26
	s_add_i32 s27, s27, s26
	s_mul_hi_u32 s26, s24, s27
	s_mul_i32 s27, s26, s10
	s_sub_i32 s24, s24, s27
	s_add_i32 s28, s26, 1
	s_sub_i32 s27, s24, s10
	s_cmp_ge_u32 s24, s10
	s_cselect_b32 s26, s28, s26
	s_cselect_b32 s24, s27, s24
	s_add_i32 s27, s26, 1
	s_cmp_ge_u32 s24, s10
	s_cselect_b32 s10, s27, s26
	s_xor_b32 s10, s10, s25
	s_sub_i32 s10, s10, s25
	s_mul_i32 s21, s10, s21
	s_sub_i32 s21, s20, s21
	s_lshl_b32 s24, s21, 6
	s_cmp_lg_u32 s11, 1
	s_mov_b32 s20, s24
	s_cbranch_scc1 .LBB0_877
	s_load_dwordx2 s[26:27], s[16:17], 0xe8
	s_lshl_b32 s20, s21, 5
	s_and_b32 s11, s21, 2
	s_and_b32 s20, s20, 0xffffff80
	s_and_b32 s21, s24, 64
	s_or_b32 s20, s20, s21
	s_cmp_eq_u32 s11, 0
	s_waitcnt lgkmcnt(0)
	s_cselect_b32 s19, s19, s27
	s_cselect_b32 s18, s18, s26

.Ltsb_skip_1:
	s_mov_b32 s98, 1
	v_add_u32_e32 v10, s20, v18
	s_lshl_b32 s25, s10, 6
	v_cmp_gt_i32_e32 vcc, s9, v10
	v_mov_b32_e32 v10, 0
	v_mov_b32_e32 v11, 0
	v_mov_b32_e32 v12, 0
	v_mov_b32_e32 v13, 0
	v_mov_b32_e32 v14, 0
	v_mov_b32_e32 v15, 0
	v_mov_b32_e32 v16, 0
	v_mov_b32_e32 v17, 0
	s_and_saveexec_b64 s[10:11], vcc
	s_cbranch_execz .LBB0_874
	v_or_b32_e32 v12, s25, v19
	v_mad_i64_i32 v[10:11], s[26:27], v12, s9, 0
	s_ashr_i32 s21, s20, 31
	v_lshl_add_u64 v[10:11], v[10:11], 2, s[18:19]
	s_lshl_b64 s[20:21], s[20:21], 2
	v_lshl_add_u64 v[10:11], v[10:11], 0, s[20:21]
	v_lshl_add_u64 v[26:27], v[10:11], 0, v[20:21]
	v_add_u32_e32 v10, 32, v12
	v_mad_i64_i32 v[10:11], s[26:27], v10, s9, 0
	v_lshl_add_u64 v[10:11], v[10:11], 2, s[18:19]
	v_lshl_add_u64 v[10:11], v[10:11], 0, s[20:21]
	v_lshl_add_u64 v[28:29], v[10:11], 0, v[20:21]
	global_load_dwordx4 v[10:13], v[26:27], off
	global_load_dwordx4 v[14:17], v[28:29], off
	s_branch .LBB0_874
.LBB0_879:
	s_waitcnt vmcnt(0)
	s_cmp_gt_i32 s73, 9
	s_cselect_b64 s[6:7], -1, 0
	s_and_b64 s[2:3], s[4:5], s[6:7]
	s_andn2_b64 vcc, exec, s[2:3]
	s_cbranch_vccnz .LBB0_933
	s_waitcnt vmcnt(0)
	s_waitcnt vmcnt(0)
	s_barrier
	s_and_saveexec_b64 s[4:5], s[86:87]
	s_cbranch_execz .LBB0_932
	s_add_i32 s2, 0, 0x25f00
	v_mov_b32_e32 v2, s2
	s_waitcnt vmcnt(0) expcnt(0) lgkmcnt(0)
	ds_read_b32 v4, v2
	s_add_i32 s2, 0, 0x25f04
	v_mov_b32_e32 v2, s2
	ds_read_b32 v2, v2
	s_waitcnt lgkmcnt(1)
	v_cmp_ne_u32_e32 vcc, 0, v4
	s_cbranch_vccnz .LBB0_896
	v_readlane_b32 s8, v250, 0
	v_readlane_b32 s9, v250, 1
	s_load_dwordx2 s[2:3], s[8:9], 0x4
	s_add_u32 s8, s74, 0x1000
	s_addc_u32 s9, s75, 0
	s_add_u32 s10, s74, 0x1100
	s_addc_u32 s11, s75, 0
	s_add_u32 s12, s74, 0x1200
	s_addc_u32 s13, s75, 0
	s_waitcnt lgkmcnt(0)
	s_mul_i32 s2, s2, s80
	s_add_u32 s14, s74, 0x1300
	s_mul_i32 s2, s2, s3
	s_addc_u32 s15, s75, 0
	s_mov_b32 s3, 1
	v_mov_b32_e32 v18, 0
	s_branch .LBB0_884

.LBB0_1100:
	s_or_b64 exec, exec, s[16:17]
	v_lshlrev_b32_e32 v10, 3, v0
	v_and_b32_e32 v10, 56, v10
	v_lshl_add_u32 v11, v10, 2, 0
	v_lshl_add_u32 v12, v19, 2, 0
	v_mul_u32_u24_e32 v13, 0x104, v147
	v_mov_b32_e32 v21, 0
	v_mul_u32_u24_e32 v14, 0x104, v18
	s_movk_i32 s23, 0x9a00
	v_lshlrev_b32_e32 v20, 2, v18
	v_add_u32_e32 v24, v12, v14
	v_add_u32_e32 v25, v11, v13
	v_lshlrev_b32_e32 v22, 1, v10
	v_mov_b32_e32 v23, v21
	s_mov_b32 s98, 0
	s_branch .LBB0_1102
.LBB0_1101:
	s_or_b64 exec, exec, s[10:11]
	s_load_dwordx2 s[10:11], s[16:17], 0xf0
	ds_write2_b32 v24, v2, v6 offset1:32
	ds_write2_b32 v24, v3, v7 offset0:65 offset1:97
	ds_write2_b32 v24, v4, v8 offset0:130 offset1:162
	ds_write2_b32 v24, v5, v9 offset0:195 offset1:227
	s_waitcnt lgkmcnt(0)
	s_barrier
	ds_read2_b32 v[2:3], v25 offset1:1
	ds_read2_b32 v[4:5], v25 offset0:2 offset1:3
	ds_read2_b32 v[6:7], v25 offset0:4 offset1:5
	ds_read2_b32 v[8:9], v25 offset0:6 offset1:7
	s_waitcnt lgkmcnt(3)
	v_cvt_pk_bf16_f32 v2, v2, v3
	s_waitcnt lgkmcnt(2)
	v_cvt_pk_bf16_f32 v3, v4, v5
	s_waitcnt lgkmcnt(1)
	v_cvt_pk_bf16_f32 v4, v6, v7
	v_add_u32_e32 v6, s22, v147
	v_mad_i64_i32 v[6:7], s[16:17], v6, s13, 0
	v_lshl_add_u64 v[6:7], v[6:7], 1, s[6:7]
	s_ashr_i32 s13, s12, 31
	v_lshl_add_u64 v[6:7], s[12:13], 1, v[6:7]
	s_waitcnt lgkmcnt(0)
	v_cvt_pk_bf16_f32 v5, v8, v9
	v_lshl_add_u64 v[6:7], v[6:7], 0, v[22:23]
	global_store_dwordx4 v[6:7], v[2:5], off
	s_andn2_b64 vcc, exec, s[14:15]
	s_mov_b32 s12, s25
	s_mov_b32 s22, s24
	s_mov_b32 s13, s8
	s_mov_b64 s[6:7], s[10:11]
	s_barrier
	s_cbranch_vccz .LBB0_1106

.LBB0_1106:
	s_waitcnt vmcnt(0)
	s_load_dwordx2 s[2:3], s[0:1], 0x310
	s_waitcnt lgkmcnt(0)
	s_cmp_gt_i32 s3, 12
	s_cselect_b64 s[6:7], -1, 0
	s_and_b64 s[2:3], s[4:5], s[6:7]
	s_andn2_b64 vcc, exec, s[2:3]
	s_cbranch_vccnz .LBB0_1160
	s_waitcnt vmcnt(0)
	s_waitcnt vmcnt(0)
	s_barrier
	s_and_saveexec_b64 s[4:5], s[86:87]
	s_cbranch_execz .LBB0_1159
	s_add_i32 s2, 0, 0x25f00
	v_mov_b32_e32 v2, s2
	s_waitcnt vmcnt(0) expcnt(0) lgkmcnt(0)
	ds_read_b32 v4, v2
	s_add_i32 s2, 0, 0x25f04
	v_mov_b32_e32 v2, s2
	ds_read_b32 v2, v2
	s_waitcnt lgkmcnt(1)
	v_cmp_ne_u32_e32 vcc, 0, v4
	s_cbranch_vccnz .LBB0_1123
	v_readlane_b32 s8, v250, 0
	v_readlane_b32 s9, v250, 1
	s_load_dwordx2 s[2:3], s[8:9], 0x4
	s_add_u32 s8, s74, 0x1000
	s_addc_u32 s9, s75, 0
	s_add_u32 s10, s74, 0x1100
	s_addc_u32 s11, s75, 0
	s_add_u32 s12, s74, 0x1200
	s_addc_u32 s13, s75, 0
	s_waitcnt lgkmcnt(0)
	s_mul_i32 s2, s2, s80
	s_add_u32 s14, s74, 0x1300
	s_mul_i32 s2, s2, s3
	s_addc_u32 s15, s75, 0
	s_mov_b32 s3, 1
	v_mov_b32_e32 v18, 0
	s_branch .LBB0_1111

.LBB0_1308:
	s_or_b64 exec, exec, s[16:17]
	v_lshlrev_b32_e32 v10, 3, v0
	v_and_b32_e32 v10, 56, v10
	v_lshl_add_u32 v11, v10, 2, 0
	v_lshl_add_u32 v12, v19, 2, 0
	v_mul_u32_u24_e32 v13, 0x104, v143
	v_mov_b32_e32 v21, 0
	v_mul_u32_u24_e32 v14, 0x104, v18
	s_movk_i32 s23, 0x9a00
	v_lshlrev_b32_e32 v20, 2, v18
	v_add_u32_e32 v24, v12, v14
	v_add_u32_e32 v25, v11, v13
	v_lshlrev_b32_e32 v22, 1, v10
	v_mov_b32_e32 v23, v21
	s_mov_b32 s98, 0
	s_branch .LBB0_1310
.LBB0_1309:
	s_or_b64 exec, exec, s[10:11]
	s_load_dwordx2 s[10:11], s[16:17], 0xf0
	ds_write2_b32 v24, v2, v6 offset1:32
	ds_write2_b32 v24, v3, v7 offset0:65 offset1:97
	ds_write2_b32 v24, v4, v8 offset0:130 offset1:162
	ds_write2_b32 v24, v5, v9 offset0:195 offset1:227
	s_waitcnt lgkmcnt(0)
	s_barrier
	ds_read2_b32 v[2:3], v25 offset1:1
	ds_read2_b32 v[4:5], v25 offset0:2 offset1:3
	ds_read2_b32 v[6:7], v25 offset0:4 offset1:5
	ds_read2_b32 v[8:9], v25 offset0:6 offset1:7
	s_waitcnt lgkmcnt(3)
	v_cvt_pk_bf16_f32 v2, v2, v3
	s_waitcnt lgkmcnt(2)
	v_cvt_pk_bf16_f32 v3, v4, v5
	s_waitcnt lgkmcnt(1)
	v_cvt_pk_bf16_f32 v4, v6, v7
	v_add_u32_e32 v6, s22, v143
	v_mad_i64_i32 v[6:7], s[16:17], v6, s13, 0
	v_lshl_add_u64 v[6:7], v[6:7], 1, s[6:7]
	s_ashr_i32 s13, s12, 31
	v_lshl_add_u64 v[6:7], s[12:13], 1, v[6:7]
	s_waitcnt lgkmcnt(0)
	v_cvt_pk_bf16_f32 v5, v8, v9
	v_lshl_add_u64 v[6:7], v[6:7], 0, v[22:23]
	global_store_dwordx4 v[6:7], v[2:5], off
	s_and_b64 vcc, exec, s[14:15]
	s_mov_b32 s12, s25
	s_mov_b32 s22, s24
	s_mov_b32 s13, s8
	s_mov_b64 s[6:7], s[10:11]
	s_barrier
	s_cbranch_vccnz .LBB0_1314

.LBB0_1314:
	s_waitcnt vmcnt(0)
	s_load_dwordx2 s[2:3], s[0:1], 0x310
	s_waitcnt lgkmcnt(0)
	s_cmp_gt_i32 s3, 14
	s_cselect_b64 s[6:7], -1, 0
	s_and_b64 s[2:3], s[4:5], s[6:7]
	s_andn2_b64 vcc, exec, s[2:3]
	s_cbranch_vccnz .LBB0_1368
	s_waitcnt vmcnt(0)
	s_waitcnt vmcnt(0)
	s_barrier
	s_and_saveexec_b64 s[4:5], s[86:87]
	s_cbranch_execz .LBB0_1367
	s_add_i32 s2, 0, 0x25f00
	v_mov_b32_e32 v2, s2
	s_waitcnt vmcnt(0) expcnt(0) lgkmcnt(0)
	ds_read_b32 v4, v2
	s_add_i32 s2, 0, 0x25f04
	v_mov_b32_e32 v2, s2
	ds_read_b32 v2, v2
	s_waitcnt lgkmcnt(1)
	v_cmp_ne_u32_e32 vcc, 0, v4
	s_cbranch_vccnz .LBB0_1331
	v_readlane_b32 s8, v250, 0
	v_readlane_b32 s9, v250, 1
	s_load_dwordx2 s[2:3], s[8:9], 0x4
	s_add_u32 s8, s74, 0x1000
	s_addc_u32 s9, s75, 0
	s_add_u32 s10, s74, 0x1100
	s_addc_u32 s11, s75, 0
	s_add_u32 s12, s74, 0x1200
	s_addc_u32 s13, s75, 0
	s_waitcnt lgkmcnt(0)
	s_mul_i32 s2, s2, s80
	s_add_u32 s14, s74, 0x1300
	s_mul_i32 s2, s2, s3
	s_addc_u32 s15, s75, 0
	s_mov_b32 s3, 1
	v_mov_b32_e32 v18, 0
	s_branch .LBB0_1319

.LBB0_2287:
	s_or_b64 exec, exec, s[14:15]
	v_lshlrev_b32_e32 v10, 3, v0
	v_and_b32_e32 v10, 56, v10
	v_lshl_add_u32 v11, v10, 2, 0
	v_lshl_add_u32 v12, v19, 2, 0
	v_mul_u32_u24_e32 v13, 0x104, v148
	v_mov_b32_e32 v21, 0
	v_mul_u32_u24_e32 v14, 0x104, v18
	s_movk_i32 s9, 0x9a00
	v_lshlrev_b32_e32 v20, 2, v18
	v_add_u32_e32 v24, v12, v14
	v_add_u32_e32 v25, v11, v13
	v_lshlrev_b32_e32 v22, 1, v10
	v_mov_b32_e32 v23, v21
	s_mov_b32 s98, 0
	s_branch .LBB0_2289
.LBB0_2288:
	s_or_b64 exec, exec, s[14:15]
	s_load_dwordx2 s[14:15], s[18:19], 0xf0
	ds_write2_b32 v24, v2, v6 offset1:32
	ds_write2_b32 v24, v3, v7 offset0:65 offset1:97
	ds_write2_b32 v24, v4, v8 offset0:130 offset1:162
	ds_write2_b32 v24, v5, v9 offset0:195 offset1:227
	s_waitcnt lgkmcnt(0)
	s_barrier
	ds_read2_b32 v[2:3], v25 offset1:1
	ds_read2_b32 v[4:5], v25 offset0:2 offset1:3
	ds_read2_b32 v[6:7], v25 offset0:4 offset1:5
	ds_read2_b32 v[8:9], v25 offset0:6 offset1:7
	s_waitcnt lgkmcnt(3)
	v_cvt_pk_bf16_f32 v2, v2, v3
	s_waitcnt lgkmcnt(2)
	v_cvt_pk_bf16_f32 v3, v4, v5
	s_waitcnt lgkmcnt(1)
	v_cvt_pk_bf16_f32 v4, v6, v7
	v_add_u32_e32 v6, s24, v148
	v_mad_i64_i32 v[6:7], s[18:19], v6, s8, 0
	v_lshl_add_u64 v[6:7], v[6:7], 1, s[6:7]
	s_ashr_i32 s11, s10, 31
	v_lshl_add_u64 v[6:7], s[10:11], 1, v[6:7]
	s_waitcnt lgkmcnt(0)
	v_cvt_pk_bf16_f32 v5, v8, v9
	v_lshl_add_u64 v[6:7], v[6:7], 0, v[22:23]
	global_store_dwordx4 v[6:7], v[2:5], off
	s_andn2_b64 vcc, exec, s[16:17]
	s_mov_b32 s10, s26
	s_mov_b32 s24, s25
	s_mov_b32 s8, s12
	s_mov_b64 s[6:7], s[14:15]
	s_barrier
	s_cbranch_vccz .LBB0_2293
.LBB0_2289:
	s_mov_b32 s11, s3
	s_add_i32 s3, s3, 1
	s_cmp_ge_i32 s3, s2
	s_cselect_b64 s[16:17], -1, 0
	s_cmp_lt_i32 s3, s2
	s_cselect_b32 s11, s3, s11
	s_cmpk_lt_u32 s11, 0x6600
	s_cselect_b32 s12, 12, 13
	s_add_i32 s13, s11, 0xfffff000
	s_cmpk_lt_u32 s13, 0x5600
	s_cselect_b32 s13, 0xfffff000, s9
	s_cmpk_gt_i32 s11, 0xfff
	s_cselect_b32 s12, s12, 11
	s_cselect_b32 s13, s13, 0
	s_add_i32 s22, s13, s11
	s_mul_i32 s12, s12, 40
	s_add_u32 s18, s0, s12
	s_addc_u32 s19, s1, 0
	s_load_dwordx4 s[12:15], s[18:19], 0xf8
	s_load_dwordx2 s[20:21], s[18:19], 0xe0
	s_abs_i32 s23, s22
	s_waitcnt lgkmcnt(0)
	s_ashr_i32 s14, s14, 6
	s_abs_i32 s11, s14
	v_cvt_f32_u32_e32 v251, s11
	s_sub_i32 s26, 0, s11
	s_xor_b32 s25, s22, s14
	s_ashr_i32 s25, s25, 31
	v_rcp_iflag_f32_e32 v251, v251
	s_nop 0
	v_mul_f32_e32 v251, 0x4f7ffffe, v251
	v_cvt_u32_f32_e32 v251, v251
	s_nop 0
	v_readfirstlane_b32 s27, v251
	s_mul_i32 s26, s26, s27
	s_mul_hi_u32 s26, s27, s26
	s_add_i32 s27, s27, s26
	s_mul_hi_u32 s26, s23, s27
	s_mul_i32 s27, s26, s11
	s_sub_i32 s23, s23, s27
	s_add_i32 s28, s26, 1
	s_sub_i32 s27, s23, s11
	s_cmp_ge_u32 s23, s11
	s_cselect_b32 s26, s28, s26
	s_cselect_b32 s23, s27, s23
	s_add_i32 s27, s26, 1
	s_cmp_ge_u32 s23, s11
	s_cselect_b32 s11, s27, s26
	s_xor_b32 s11, s11, s25
	s_sub_i32 s11, s11, s25
	s_mul_i32 s14, s11, s14
	s_sub_i32 s14, s22, s14
	s_lshl_b32 s25, s14, 6
	s_cmp_lg_u32 s15, 1
	s_mov_b32 s22, s25
	s_cbranch_scc1 .LBB0_2291
	s_and_b32 s23, s14, 2
	s_lshl_b32 s22, s14, 5
	s_load_dwordx2 s[14:15], s[18:19], 0xe8
	s_and_b32 s22, s22, 0xffffff80
	s_and_b32 s26, s25, 64
	s_or_b32 s22, s22, s26
	s_cmp_eq_u32 s23, 0
	s_waitcnt lgkmcnt(0)
	s_cselect_b32 s21, s21, s15
	s_cselect_b32 s20, s20, s14

.Ltsb_skip_4:
	s_mov_b32 s98, 1
	v_add_u32_e32 v10, s22, v18
	s_lshl_b32 s26, s11, 6
	v_cmp_gt_i32_e32 vcc, s13, v10
	v_mov_b32_e32 v10, 0
	v_mov_b32_e32 v11, 0
	v_mov_b32_e32 v12, 0
	v_mov_b32_e32 v13, 0
	v_mov_b32_e32 v14, 0
	v_mov_b32_e32 v15, 0
	v_mov_b32_e32 v16, 0
	v_mov_b32_e32 v17, 0
	s_and_saveexec_b64 s[14:15], vcc
	s_cbranch_execz .LBB0_2288
	v_or_b32_e32 v12, s26, v19
	v_mad_i64_i32 v[10:11], s[28:29], v12, s13, 0
	s_ashr_i32 s23, s22, 31
	v_lshl_add_u64 v[10:11], v[10:11], 2, s[20:21]
	s_lshl_b64 s[22:23], s[22:23], 2
	v_lshl_add_u64 v[10:11], v[10:11], 0, s[22:23]
	v_lshl_add_u64 v[26:27], v[10:11], 0, v[20:21]
	v_add_u32_e32 v10, 32, v12
	v_mad_i64_i32 v[10:11], s[28:29], v10, s13, 0
	v_lshl_add_u64 v[10:11], v[10:11], 2, s[20:21]
	v_lshl_add_u64 v[10:11], v[10:11], 0, s[22:23]
	v_lshl_add_u64 v[28:29], v[10:11], 0, v[20:21]
	global_load_dwordx4 v[10:13], v[26:27], off
	global_load_dwordx4 v[14:17], v[28:29], off
	s_branch .LBB0_2288
.LBB0_2293:
	s_waitcnt vmcnt(0)
	s_cmp_gt_i32 s57, 21
	s_cselect_b64 s[6:7], -1, 0
	s_and_b64 s[2:3], s[4:5], s[6:7]
	s_andn2_b64 vcc, exec, s[2:3]
	s_cbranch_vccnz .LBB0_2347
	s_waitcnt vmcnt(0)
	s_waitcnt vmcnt(0)
	s_barrier
	s_and_saveexec_b64 s[4:5], s[86:87]
	s_cbranch_execz .LBB0_2346
	s_add_i32 s2, 0, 0x25f00
	v_mov_b32_e32 v2, s2
	s_waitcnt vmcnt(0) expcnt(0) lgkmcnt(0)
	ds_read_b32 v4, v2
	s_add_i32 s2, 0, 0x25f04
	v_mov_b32_e32 v2, s2
	ds_read_b32 v2, v2
	s_waitcnt lgkmcnt(1)
	v_cmp_ne_u32_e32 vcc, 0, v4
	s_cbranch_vccnz .LBB0_2310
	v_readlane_b32 s8, v250, 0
	v_readlane_b32 s9, v250, 1
	s_load_dwordx2 s[2:3], s[8:9], 0x4
	s_add_u32 s8, s74, 0x1000
	s_addc_u32 s9, s75, 0
	s_add_u32 s10, s74, 0x1100
	s_addc_u32 s11, s75, 0
	s_add_u32 s12, s74, 0x1200
	s_addc_u32 s13, s75, 0
	s_waitcnt lgkmcnt(0)
	s_mul_i32 s2, s2, s80
	s_add_u32 s14, s74, 0x1300
	s_mul_i32 s2, s2, s3
	s_addc_u32 s15, s75, 0
	s_mov_b32 s3, 1
	v_mov_b32_e32 v18, 0
	s_branch .LBB0_2298

	.amdhsa_kernel _Z3fwd4Args
		.amdhsa_group_segment_fixed_size 0
		.amdhsa_private_segment_fixed_size 0
		.amdhsa_kernarg_size 1048
		.amdhsa_user_sgpr_count 2
		.amdhsa_user_sgpr_dispatch_ptr 0
		.amdhsa_user_sgpr_queue_ptr 0
		.amdhsa_user_sgpr_kernarg_segment_ptr 1
		.amdhsa_user_sgpr_dispatch_id 0
		.amdhsa_user_sgpr_kernarg_preload_length 0
		.amdhsa_user_sgpr_kernarg_preload_offset 0
		.amdhsa_user_sgpr_private_segment_size 0
		.amdhsa_uses_dynamic_stack 0
		.amdhsa_enable_private_segment 0
		.amdhsa_system_sgpr_workgroup_id_x 1
		.amdhsa_system_sgpr_workgroup_id_y 0
		.amdhsa_system_sgpr_workgroup_id_z 0
		.amdhsa_system_sgpr_workgroup_info 0
		.amdhsa_system_vgpr_workitem_id 0
		.amdhsa_next_free_vgpr 256
		.amdhsa_next_free_sgpr 102
		.amdhsa_accum_offset 256
		.amdhsa_reserve_vcc 1
		.amdhsa_float_round_mode_32 0
		.amdhsa_float_round_mode_16_64 0
		.amdhsa_float_denorm_mode_32 3
		.amdhsa_float_denorm_mode_16_64 3
		.amdhsa_dx10_clamp 1
		.amdhsa_ieee_mode 1
		.amdhsa_fp16_overflow 0
		.amdhsa_tg_split 0
		.amdhsa_exception_fp_ieee_invalid_op 0
		.amdhsa_exception_fp_denorm_src 0
		.amdhsa_exception_fp_ieee_div_zero 0
		.amdhsa_exception_fp_ieee_overflow 0
		.amdhsa_exception_fp_ieee_underflow 0
		.amdhsa_exception_fp_ieee_inexact 0
		.amdhsa_exception_int_div_zero 0
	.end_amdhsa_kernel

amdhsa.kernels:
  - .agpr_count:     0
    .args:
      - .offset:         0
        .size:           792
        .value_kind:     by_value
      - .offset:         792
        .size:           4
        .value_kind:     hidden_block_count_x
      - .offset:         796
        .size:           4
        .value_kind:     hidden_block_count_y
      - .offset:         800
        .size:           4
        .value_kind:     hidden_block_count_z
      - .offset:         804
        .size:           2
        .value_kind:     hidden_group_size_x
      - .offset:         806
        .size:           2
        .value_kind:     hidden_group_size_y
      - .offset:         808
        .size:           2
        .value_kind:     hidden_group_size_z
      - .offset:         810
        .size:           2
        .value_kind:     hidden_remainder_x
      - .offset:         812
        .size:           2
        .value_kind:     hidden_remainder_y
      - .offset:         814
        .size:           2
        .value_kind:     hidden_remainder_z
      - .offset:         832
        .size:           8
        .value_kind:     hidden_global_offset_x
      - .offset:         840
        .size:           8
        .value_kind:     hidden_global_offset_y
      - .offset:         848
        .size:           8
        .value_kind:     hidden_global_offset_z
      - .offset:         856
        .size:           2
        .value_kind:     hidden_grid_dims
      - .offset:         912
        .size:           4
        .value_kind:     hidden_dynamic_lds_size
    .group_segment_fixed_size: 0
    .kernarg_segment_align: 8
    .kernarg_segment_size: 1048
    .language:       OpenCL C
    .language_version:
      - 2
      - 0
    .max_flat_workgroup_size: 512
    .name:           _Z3fwd4Args
    .private_segment_fixed_size: 0
    .sgpr_count:     108
    .sgpr_spill_count: 38
    .symbol:         _Z3fwd4Args.kd
    .uniform_work_group_size: 1
    .uses_dynamic_stack: false
    .vgpr_count:     256
    .vgpr_spill_count: 0
    .wavefront_size: 64
